# hand-written weight-conversion chunk body also in the prologue (layer 0)
# baseline (speedup 1.0000x reference)
; #define LAS __attribute__((address_space(3)))
;     LAS bf16_t* T = (LAS bf16_t*)sm;
;     const int kk = tid >> 3, nq = tid & 7;
;     f32x4 c0 = (f32x4){0.f, 0.f, 0.f, 0.f}, c1 = c0;
;     int t = t_begin + wgi;
;     if (t < t_end) { const CvtMat m = cvt_mat_of(L, t, ws, ap); const int nb = m.N / 64, k0 = 64 * (m.tm / nb), n0 = 64 * (m.tm % nb);
;         c0 = cvt_src4(m.kind, m.src, m.src2, m.gain, m.ld, k0 + kk, n0 + 8 * nq); c1 = cvt_src4(m.kind, m.src, m.src2, m.gain, m.ld, k0 + kk, n0 + 8 * nq + 4); }
;     for (; t < t_end; t += nwg) {
;         const CvtMat m = cvt_mat_of(L, t, ws, ap); const int nb = m.N / 64, k0 = 64 * (m.tm / nb), n0 = 64 * (m.tm % nb);
; __global__ void __launch_bounds__(512, 2) mk_fwd(MKArgs args) {
;     ...
;         cvt_layer_wg(0, bx, G, tid, ldsl + RING_OFF, ws, ap);
.LBB0_8:
	s_or_b64 exec, exec, s[0:1]
	v_readlane_b32 s0, v254, 1
	v_readlane_b32 s1, v254, 2
	s_mov_b64 s[16:17], s[0:1]
	s_load_dword s30, s[0:1], 0x138
	s_add_u32 s2, s0, 0x138
	s_addc_u32 s3, s1, 0
	v_writelane_b32 v254, s2, 9
	s_mov_b32 s22, 0
	s_waitcnt lgkmcnt(0)
	s_mov_b32 s31, s30
	v_writelane_b32 v254, s3, 10
	s_load_dwordx2 s[0:1], s[16:17], 0x120
	v_readlane_b32 s90, v254, 0
	s_load_dwordx2 s[2:3], s[16:17], 0x0
	v_readlane_b32 s4, v254, 3
	v_mbcnt_lo_u32_b32 v0, -1, 0
	v_mbcnt_hi_u32_b32 v0, -1, v0
	s_cmpk_lt_i32 s90, 0xb40
	s_nop 0
	v_add_u32_e32 v54, s4, v0
	s_cselect_b64 s[4:5], -1, 0
	v_readfirstlane_b32 s91, v54
	v_ashrrev_i32_e32 v13, 3, v54
	s_waitcnt lgkmcnt(0)
	s_mov_b32 s48, s90
.Lcvp_loop:
	s_cmpk_gt_u32 s48, 0x2cf
	s_cbranch_scc1 .LBB0_295
	s_mov_b32 s49, 0
	s_cmpk_lt_u32 s48, 0x60
	s_cselect_b64 s[50:51], -1, 0
	s_movk_i32 s62, 0x100
	s_mov_b32 s64, 0
	s_mov_b32 s65, 0
	s_mov_b32 s70, 0
	s_mov_b32 s7, 0
	s_movk_i32 s71, 0x7fff
	s_mov_b32 s72, 0
	s_cmpk_lt_u32 s48, 0x60
	s_cbranch_scc1 .Lcvp_win
	s_cmpk_lt_u32 s48, 0x6c
	s_cbranch_scc1 .Lcvp_wqb
	s_cmpk_lt_u32 s48, 0x7c
	s_cbranch_scc1 .Lcvp_wkv
	s_cmpk_lt_u32 s48, 0x80
	s_cbranch_scc1 .Lcvp_glu
	s_cmpk_lt_u32 s48, 0xc0
	s_cbranch_scc1 .Lcvp_wout
	s_cmpk_lt_u32 s48, 0x220
	s_cbranch_scc1 .Lcvp_ffi
	s_add_i32 s6, s48, 0xfffffde0
	s_lshr_b32 s73, s6, 2
	s_and_b32 s6, s6, 3
	s_load_dwordx2 s[14:15], s[16:17], 0x108
	s_mul_i32 s10, s49, 0xb00000
	s_movk_i32 s56, 0x1000
	s_movk_i32 s60, 0x1600
	s_add_u32 s58, s0, 0x1200000
	s_addc_u32 s59, s1, 0
	s_lshl_b32 s63, s6, 10
	s_waitcnt lgkmcnt(0)
	s_add_u32 s52, s14, s10
	s_addc_u32 s53, s15, 0
	s_branch .Lcvp_common
.Lcvp_win:
	s_mul_hi_u32 s73, s48, 0xaaaaaaab
	s_lshr_b32 s73, s73, 2
	s_mul_i32 s6, s73, 6
	s_sub_u32 s6, s48, s6
	s_load_dwordx4 s[12:15], s[16:17], 0x40
	s_mul_i32 s10, s49, 0x5b0000
	s_lshl_b32 s11, s49, 12
	s_movk_i32 s56, 0x16c0
	s_movk_i32 s60, 0x800
	s_add_u32 s58, s0, 0x100000
	s_addc_u32 s59, s1, 0
	s_mov_b32 s72, 1
	s_lshl_b32 s63, s6, 10
	s_cmp_lt_u32 s6, 3
	s_cbranch_scc1 .Lcvp_win_a
	s_add_i32 s63, s63, 0xfffffe80

; #define KPTR(T, ap64, i) ((T*)(__attribute__((address_space(1))) T*)(ap64)[i])
; template <class AP> DEV CvtMat cvt_mat_of(int L, int t, unsigned char* ws, AP ap) {
;     unsigned char* wl = ws + WS_W + (size_t)L * WL_SIZE; CvtMat m;
;     if (t < 384) { m = CvtMat{KPTR(const float, ap, 9) + (size_t)L * DM * DIN, nullptr, KPTR(const float, ap, 8) + L * DM, (bf16_t*)(wl + WL_IN), CV_WIN, DINP, DM, 0, t}; }
;     else if (t < 432) { m = CvtMat{KPTR(const float, ap, 21) + (size_t)L * 256 * 768, nullptr, KPTR(const float, ap, 20) + L * 256, (bf16_t*)(wl + WL_QB), CV_WQB, 768, 256, 0, t - 384}; }
.Lcvp_wqb:
	s_add_i32 s6, s48, 0xffffffa0
	s_mul_hi_u32 s73, s6, 0xaaaaaaab
	s_lshr_b32 s73, s73, 1
	s_mul_i32 s10, s73, 3
	s_sub_u32 s6, s6, s10
	s_load_dwordx4 s[12:15], s[16:17], 0xa0
	s_mul_i32 s10, s49, 0xc0000
	s_lshl_b32 s11, s49, 10
	s_movk_i32 s56, 0xc00
	s_movk_i32 s60, 0x200
	s_add_u32 s58, s0, 0x400000
	s_addc_u32 s59, s1, 0
	s_mov_b32 s72, 1
	s_mul_i32 s63, s6, 0x600
	s_movk_i32 s70, 0x80
	s_cmp_lg_u32 s6, 2
	s_cbranch_scc1 .Lcvp_wqb_a
	s_mov_b32 s72, 3
	s_movk_i32 s70, 0x200
	s_mov_b32 s7, 48

; #define KPTR(T, ap64, i) ((T*)(__attribute__((address_space(1))) T*)(ap64)[i])
; template <class AP> DEV CvtMat cvt_mat_of(int L, int t, unsigned char* ws, AP ap) {
;     ...
;     else if (t < 496) { m = CvtMat{KPTR(const float, ap, 23) + (size_t)L * 128 * 512, KPTR(const float, ap, 24) + (size_t)L * 128 * 512, KPTR(const float, ap, 22) + L * 128, (bf16_t*)(wl + WL_KV), CV_WKV, 1024, 256, 0, t - 432}; }
;     else if (t < 512) { m = CvtMat{KPTR(const float, ap, 18) + (size_t)L * 65536, nullptr, nullptr, (bf16_t*)(wl + WL_GLU), CV_T, 256, 256, 256, t - 496}; }
;     else if (t < 768) { m = CvtMat{KPTR(const float, ap, 28) + (size_t)L * DM * DM, nullptr, nullptr, (bf16_t*)(wl + WL_OUT), CV_T, DM, DM, DM, t - 512}; }
;     else if (t < 2176) { m = CvtMat{KPTR(const float, ap, 30) + (size_t)L * DM * DFF2, nullptr, KPTR(const float, ap, 29) + L * DM, (bf16_t*)(wl + WL_FFI), CV_WFFI, DFF2, DM, 0, t - 768}; }
.Lcvp_wkv:
	s_add_i32 s6, s48, 0xffffff94
	s_lshr_b32 s73, s6, 2
	s_and_b32 s6, s6, 3
	s_load_dwordx4 s[12:15], s[16:17], 0xb0
	s_load_dwordx2 s[10:11], s[16:17], 0xc0
	s_lshl_b32 s80, s49, 18
	s_lshl_b32 s81, s49, 9
	s_movk_i32 s56, 0x800
	s_movk_i32 s60, 0x200
	s_add_u32 s58, s0, 0x460000
	s_addc_u32 s59, s1, 0
	s_mov_b32 s72, 1
	s_movk_i32 s71, 0x80
	s_and_b32 s63, s6, 1
	s_lshl_b32 s63, s63, 10
	s_waitcnt lgkmcnt(0)
	s_cmp_lt_u32 s6, 2
	s_cselect_b32 s14, s14, s10
	s_cselect_b32 s15, s15, s11
	s_add_u32 s52, s14, s80
	s_addc_u32 s53, s15, 0
	s_add_u32 s54, s12, s81
	s_addc_u32 s55, s13, 0
	s_branch .Lcvp_common
.Lcvp_glu:
	s_add_i32 s73, s48, 0xffffff84
	s_mov_b32 s6, 0
	s_load_dwordx2 s[14:15], s[16:17], 0x90
	s_lshl_b32 s10, s49, 18
	s_movk_i32 s56, 0x400
	s_movk_i32 s60, 0x200
	s_add_u32 s58, s0, 0x4e0000
	s_addc_u32 s59, s1, 0
	s_mov_b32 s63, 0
	s_waitcnt lgkmcnt(0)
	s_add_u32 s52, s14, s10
	s_addc_u32 s53, s15, 0
	s_branch .Lcvp_common
.Lcvp_wout:
	s_add_i32 s6, s48, 0xffffff80
	s_lshr_b32 s73, s6, 2
	s_and_b32 s6, s6, 3
	s_load_dwordx2 s[14:15], s[16:17], 0xe0
	s_lshl_b32 s10, s49, 22
	s_movk_i32 s56, 0x1000
	s_movk_i32 s60, 0x800
	s_add_u32 s58, s0, 0x500000
	s_addc_u32 s59, s1, 0
	s_lshl_b32 s63, s6, 10
	s_waitcnt lgkmcnt(0)
	s_add_u32 s52, s14, s10
	s_addc_u32 s53, s15, 0
	s_branch .Lcvp_common
.Lcvp_ffi:
	s_add_i32 s6, s48, 0xffffff40
	s_mul_hi_u32 s73, s6, 0xba2e8ba3
	s_lshr_b32 s73, s73, 4
	s_mul_i32 s10, s73, 22
	s_sub_u32 s6, s6, s10
	s_load_dwordx4 s[12:15], s[16:17], 0xe8
	s_mul_i32 s10, s49, 0x1600000
	s_lshl_b32 s11, s49, 12
	s_movk_i32 s56, 0x5800
	s_movk_i32 s60, 0x800
	s_add_u32 s58, s0, 0x700000
	s_addc_u32 s59, s1, 0
	s_mov_b32 s72, 1
	s_movk_i32 s62, 0x80
	s_movk_i32 s64, 0x100
	s_lshl_b32 s63, s6, 9
	s_add_i32 s65, s63, 0x2a00
	s_waitcnt lgkmcnt(0)
	s_add_u32 s52, s14, s10
	s_addc_u32 s53, s15, 0
	s_add_u32 s54, s12, s11
	s_addc_u32 s55, s13, 0

; DEV bf16_t f2bf(float f) { unsigned u = __float_as_uint(f); u += 0x7fffu + ((u >> 16) & 1u); return (bf16_t)(u >> 16); }
; DEV void lds_barrier() { asm volatile("s_waitcnt lgkmcnt(0)" ::: "memory"); __builtin_amdgcn_s_barrier(); asm volatile("" ::: "memory"); }
; #define LAS __attribute__((address_space(3)))
;     ...
;     for (; t < t_end; t += nwg) {
;         const CvtMat m = cvt_mat_of(L, t, ws, ap); const int nb = m.N / 64, k0 = 64 * (m.tm / nb), n0 = 64 * (m.tm % nb);
;         lds_barrier();
; #pragma unroll
;         for (int e = 0; e < 4; ++e) { T[(8 * nq + e) * 72 + kk] = f2bf(c0[e]); T[(8 * nq + 4 + e) * 72 + kk] = f2bf(c1[e]); }
;         if (t + nwg < t_end) { const CvtMat m2 = cvt_mat_of(L, t + nwg, ws, ap); const int nb2 = m2.N / 64, k2 = 64 * (m2.tm / nb2), n2 = 64 * (m2.tm % nb2);
;             c0 = cvt_src4(m2.kind, m2.src, m2.src2, m2.gain, m2.ld, k2 + kk, n2 + 8 * nq); c1 = cvt_src4(m2.kind, m2.src, m2.src2, m2.gain, m2.ld, k2 + kk, n2 + 8 * nq + 4); }
;         lds_barrier();
;         { const int nl = tid >> 3, kc = tid & 7; *(u32x4*)(m.dst + (size_t)(n0 + nl) * m.K + k0 + 8 * kc) = *(const LAS u32x4*)(T + nl * 72 + 8 * kc); }
;     }
.Lcvp_next:
	s_waitcnt lgkmcnt(0)
	s_barrier
	s_add_u32 s48, s48, s31
	s_branch .Lcvp_loop
